# GEMM phase prologues: K-tile-1 DMA batch issued before waiting for K-tile 0 (wait+barrier moved below the second batch)
# baseline (speedup 1.0000x reference)
.LBB0_155:
	s_lshl_b32 s6, s6, 5
	s_and_b32 s12, s6, 0x60
	s_mov_b64 s[6:7], 0x80
	s_add_i32 m0, s19, 0x18000
	v_lshl_add_u64 v[6:7], v[6:7], 0, s[6:7]
	s_ashr_i32 s43, s31, 31
	s_lshl_b32 s9, s8, 13
	s_lshl_b32 s13, s12, 7
	global_load_lds_dwordx4 v[6:7], off
	v_lshl_add_u64 v[4:5], v[4:5], 0, s[6:7]
	s_add_i32 m0, s19, 0x1a000
	s_add_i32 s44, s19, 0x8000
	s_add_i32 s45, s19, 0xa000
	global_load_lds_dwordx4 v[4:5], off
	v_lshl_add_u64 v[0:1], v[0:1], 0, s[6:7]
	s_mov_b32 m0, s44
	s_add_u32 s10, s24, 0x40080
	global_load_lds_dwordx4 v[0:1], off
	v_lshl_add_u64 v[0:1], v[2:3], 0, s[6:7]
	s_mov_b32 m0, s45
	s_addc_u32 s11, s25, 0
	global_load_lds_dwordx4 v[0:1], off
	s_add_i32 m0, s19, 0x1c000
	v_lshl_add_u64 v[0:1], s[10:11], 0, v[130:131]
	global_load_lds_dwordx4 v[0:1], off
	v_lshl_add_u64 v[0:1], s[10:11], 0, v[134:135]
	s_add_i32 m0, s19, 0x1e000
	v_bfe_u32 v3, v196, 4, 2
	global_load_lds_dwordx4 v[0:1], off
	s_sext_i32_i16 s49, s0
	v_lshlrev_b32_e32 v0, 4, v3
	v_lshlrev_b32_e32 v1, 6, v196
	s_movk_i32 s0, 0x3c0
	v_and_or_b32 v4, v1, s0, v0
	v_lshlrev_b32_e32 v1, 2, v196
	v_and_b32_e32 v5, 32, v1
	v_mov_b32_e32 v1, v131
	v_and_b32_e32 v2, 15, v196
	v_lshl_add_u64 v[136:137], s[34:35], 0, v[0:1]
	v_lshlrev_b32_e32 v1, 8, v196
	v_lshl_or_b32 v149, s8, 6, v2
	v_lshl_or_b32 v0, v2, 6, v0
	v_and_b32_e32 v1, 0x38000, v1
	v_lshlrev_b32_e32 v2, 11, v10
	v_or3_b32 v1, v8, v1, v2
	v_add_u32_e32 v138, v1, v9
	v_lshlrev_b32_e32 v1, 4, v11
	v_bitop3_b32 v0, v0, s9, v5 bitop3:0xde
	s_waitcnt vmcnt(8)
	s_barrier
	s_waitcnt vmcnt(6)
	s_cmpk_lt_u32 s1, 0x100
	v_and_b32_e32 v1, 0x78000, v1
	v_bitop3_b32 v150, s13, v4, v5 bitop3:0xf6
	s_cselect_b64 s[8:9], -1, 0
	v_or3_b32 v1, v8, v1, v2
	s_add_i32 s46, 0, 0x10000
	s_add_i32 s47, 0, 0x14000
	v_add_u32_e32 v157, 0, v0
	v_mbcnt_lo_u32_b32 v0, -1, 0
	v_or_b32_e32 v151, 16, v149
	v_or_b32_e32 v152, 32, v149
	v_or_b32_e32 v153, 48, v149
	v_lshl_or_b32 v154, v3, 3, s12
	v_mov_b32_e32 v139, v131
	v_add_u32_e32 v140, v1, v9
	v_mov_b32_e32 v141, v131
	v_mov_b64_e32 v[142:143], 0xb00
	v_mov_b64_e32 v[144:145], 0xaff
	v_add_u32_e32 v155, s46, v150
	v_add_u32_e32 v156, s47, v150
	v_mbcnt_hi_u32_b32 v158, -1, v0
	v_mov_b32_e32 v159, 0x358637bd
	s_movk_i32 s48, 0x1600
	s_barrier
	s_branch .LBB0_158

.LBB0_224:
	s_mov_b64 s[12:13], 0x80
	s_and_b32 s43, s0, 3
	s_add_i32 m0, s29, 0x18000
	v_lshl_add_u64 v[6:7], v[6:7], 0, s[12:13]
	s_ashr_i32 s41, s31, 31
	s_ashr_i32 s42, s30, 31
	s_lshl_b32 s4, s3, 13
	s_lshl_b32 s5, s43, 12
	global_load_lds_dwordx4 v[6:7], off
	v_lshl_add_u64 v[4:5], v[4:5], 0, s[12:13]
	s_add_i32 m0, s29, 0x1a000
	s_add_i32 s44, s29, 0x8000
	s_add_i32 s45, s29, 0xa000
	global_load_lds_dwordx4 v[4:5], off
	v_lshl_add_u64 v[0:1], v[0:1], 0, s[12:13]
	s_mov_b32 m0, s44
	s_add_u32 s0, s22, 0xb0080
	global_load_lds_dwordx4 v[0:1], off
	v_lshl_add_u64 v[0:1], v[2:3], 0, s[12:13]
	s_mov_b32 m0, s45
	s_addc_u32 s1, s23, 0
	global_load_lds_dwordx4 v[0:1], off
	s_add_i32 m0, s29, 0x1c000
	v_lshl_add_u64 v[0:1], s[0:1], 0, v[154:155]
	global_load_lds_dwordx4 v[0:1], off
	v_lshl_add_u64 v[0:1], s[0:1], 0, v[158:159]
	s_add_i32 m0, s29, 0x1e000
	v_lshlrev_b32_e32 v4, 6, v196
	global_load_lds_dwordx4 v[0:1], off
	v_bfe_u32 v0, v196, 4, 2
	v_and_b32_e32 v1, 15, v196
	v_lshlrev_b32_e32 v3, 4, v0
	s_movk_i32 s0, 0x3c0
	v_lshlrev_b32_e32 v5, 2, v196
	v_lshlrev_b32_e32 v2, 3, v0
	v_and_or_b32 v4, v4, s0, v3
	v_and_b32_e32 v5, 32, v5
	v_cmp_eq_u32_e64 s[0:1], 0, v0
	v_lshl_or_b32 v0, v1, 6, v3
	v_lshl_or_b32 v186, s3, 6, v1
	v_bitop3_b32 v0, v0, s4, v5 bitop3:0xde
	s_waitcnt vmcnt(8)
	s_barrier
	s_waitcnt vmcnt(6)
	s_cmpk_lt_u32 s2, 0x100
	v_add_u16_e32 v1, v8, v9
	v_bitop3_b32 v187, s5, v4, v5 bitop3:0xf6
	s_cselect_b64 s[14:15], -1, 0
	v_lshrrev_b16_e32 v1, 1, v1
	s_add_i32 s46, 0, 0x10000
	s_add_i32 s47, 0, 0x14000
	v_add_u32_e32 v191, 0, v0
	v_mbcnt_lo_u32_b32 v0, -1, 0
	v_lshl_or_b32 v188, s43, 5, v2
	v_add_lshl_u32 v160, v10, v1, 1
	v_mov_b32_e32 v161, v155
	v_add_lshl_u32 v162, v11, v1, 1
	v_mov_b32_e32 v163, v155
	v_mov_b64_e32 v[164:165], 0x200
	v_mov_b64_e32 v[166:167], 0x1ff
	v_add_u32_e32 v189, s46, v187
	v_add_u32_e32 v190, s47, v187
	v_mbcnt_hi_u32_b32 v192, -1, v0
	s_mov_b32 s48, 0
	s_barrier
	s_branch .LBB0_227

.LBB0_317:
	s_mov_b64 s[8:9], 0x80
	s_and_b32 s3, s1, 3
	s_add_i32 m0, s43, 0x18000
	v_lshl_add_u64 v[6:7], v[6:7], 0, s[8:9]
	s_ashr_i32 s48, s31, 31
	s_ashr_i32 s49, s30, 31
	s_lshl_b32 s50, s0, 6
	s_lshl_b32 s10, s0, 13
	s_lshl_b32 s11, s3, 12
	global_load_lds_dwordx4 v[6:7], off
	v_lshl_add_u64 v[4:5], v[4:5], 0, s[8:9]
	s_add_i32 m0, s43, 0x1a000
	s_add_i32 s51, s43, 0x8000
	s_add_i32 s64, s43, 0xa000
	global_load_lds_dwordx4 v[4:5], off
	v_lshl_add_u64 v[0:1], v[0:1], 0, s[8:9]
	s_mov_b32 m0, s51
	s_add_u32 s0, s28, 0x40080
	global_load_lds_dwordx4 v[0:1], off
	v_lshl_add_u64 v[0:1], v[2:3], 0, s[8:9]
	s_mov_b32 m0, s64
	s_addc_u32 s1, s29, 0
	global_load_lds_dwordx4 v[0:1], off
	s_add_i32 m0, s43, 0x1c000
	v_lshl_add_u64 v[0:1], s[0:1], 0, v[162:163]
	global_load_lds_dwordx4 v[0:1], off
	v_lshl_add_u64 v[0:1], s[0:1], 0, v[166:167]
	s_add_i32 m0, s43, 0x1e000
	v_bfe_u32 v193, v196, 4, 2
	global_load_lds_dwordx4 v[0:1], off
	v_lshlrev_b32_e32 v0, 3, v193
	v_lshlrev_b32_e32 v168, 4, v193
	v_lshlrev_b32_e32 v1, 6, v196
	s_movk_i32 s0, 0x3c0
	v_lshlrev_b32_e32 v2, 2, v196
	v_and_or_b32 v1, v1, s0, v168
	v_and_b32_e32 v2, 32, v2
	v_lshl_or_b32 v195, s3, 5, v0
	v_lshlrev_b32_e32 v0, 8, v196
	v_bitop3_b32 v194, s11, v1, v2 bitop3:0xf6
	v_and_b32_e32 v0, 0x38000, v0
	v_lshlrev_b32_e32 v1, 11, v10
	v_or3_b32 v0, v8, v0, v1
	v_and_b32_e32 v192, 15, v196
	v_add_u32_e32 v172, v0, v9
	v_lshlrev_b32_e32 v0, 4, v11
	v_lshl_or_b32 v3, v192, 6, v168
	s_cmpk_lt_u32 s12, 0x100
	v_and_b32_e32 v0, 0x78000, v0
	v_bitop3_b32 v3, v3, s10, v2 bitop3:0xde
	s_waitcnt vmcnt(8)
	s_barrier
	s_waitcnt vmcnt(6)
	s_cselect_b64 s[10:11], -1, 0
	s_bitcmp0_b32 s12, 6
	v_or3_b32 v0, v8, v0, v1
	s_cselect_b64 s[12:13], -1, 0
	v_add_u32_e32 v174, v0, v9
	s_add_i32 s66, 0, 0x10000
	s_add_i32 s67, 0, 0x14000
	v_mbcnt_lo_u32_b32 v0, -1, 0
	v_lshl_add_u64 v[170:171], s[34:35], 0, v[168:169]
	v_mov_b32_e32 v173, v169
	v_mov_b32_e32 v175, v169
	v_mov_b64_e32 v[176:177], 0x600
	v_mov_b64_e32 v[178:179], 0x5ff
	s_movk_i32 s65, 0xc1
	v_add_u32_e32 v197, s66, v194
	v_add_u32_e32 v198, s67, v194
	v_add_u32_e32 v199, 0, v3
	v_mbcnt_hi_u32_b32 v200, -1, v0
	v_mov_b32_e32 v201, 0x358637bd
	v_mov_b32_e32 v202, 0x3e38aa3b
	s_barrier
	s_branch .LBB0_320

.LBB0_786:
	s_mov_b64 s[10:11], 0x80
	s_and_b32 s65, s1, 3
	s_add_i32 m0, s49, 0x18000
	v_lshl_add_u64 v[6:7], v[6:7], 0, s[10:11]
	s_lshl_b32 s1, s0, 13
	s_lshl_b32 s13, s65, 12
	global_load_lds_dwordx4 v[6:7], off
	v_lshl_add_u64 v[4:5], v[4:5], 0, s[10:11]
	s_add_i32 m0, s49, 0x1a000
	s_add_i32 s66, s49, 0x8000
	s_add_i32 s67, s49, 0xa000
	global_load_lds_dwordx4 v[4:5], off
	v_lshl_add_u64 v[0:1], v[0:1], 0, s[10:11]
	s_mov_b32 m0, s66
	s_add_u32 s2, s28, 0x40080
	global_load_lds_dwordx4 v[0:1], off
	v_lshl_add_u64 v[0:1], v[2:3], 0, s[10:11]
	s_mov_b32 m0, s67
	s_addc_u32 s3, s29, 0
	global_load_lds_dwordx4 v[0:1], off
	s_add_i32 m0, s49, 0x1c000
	v_lshl_add_u64 v[0:1], s[2:3], 0, v[154:155]
	global_load_lds_dwordx4 v[0:1], off
	v_lshl_add_u64 v[0:1], s[2:3], 0, v[158:159]
	s_add_i32 m0, s49, 0x1e000
	v_lshlrev_b32_e32 v4, 2, v196
	global_load_lds_dwordx4 v[0:1], off
	v_bfe_u32 v0, v196, 4, 2
	v_and_b32_e32 v1, 15, v196
	v_lshlrev_b32_e32 v3, 4, v0
	s_waitcnt vmcnt(0)
	v_lshl_or_b32 v186, s0, 6, v1
	v_lshl_or_b32 v1, v1, 6, v3
	v_and_b32_e32 v4, 32, v4
	v_lshlrev_b32_e32 v5, 6, v196
	s_movk_i32 s0, 0x3c0
	v_lshlrev_b32_e32 v2, 3, v0
	v_bitop3_b32 v1, v1, s1, v4 bitop3:0xde
	v_and_or_b32 v3, v5, s0, v3
	v_cmp_eq_u32_e64 s[0:1], 0, v0
	v_lshlrev_b32_e32 v0, 8, v196
	v_lshl_or_b32 v188, s65, 5, v2
	v_and_b32_e32 v0, 0x38000, v0
	v_lshlrev_b32_e32 v2, 11, v10
	v_or3_b32 v0, v8, v0, v2
	v_add_u32_e32 v160, v0, v9
	v_lshlrev_b32_e32 v0, 4, v11
	v_and_b32_e32 v0, 0x78000, v0
	s_waitcnt vmcnt(8)
	s_barrier
	s_waitcnt vmcnt(6)
	s_cmpk_lt_u32 s12, 0x100
	v_or3_b32 v0, v8, v0, v2
	v_bitop3_b32 v187, s13, v3, v4 bitop3:0xf6
	s_cselect_b64 s[12:13], -1, 0
	v_add_u32_e32 v162, v0, v9
	s_add_i32 s70, 0, 0x10000
	s_add_i32 s71, 0, 0x14000
	v_mbcnt_lo_u32_b32 v0, -1, 0
	s_ashr_i32 s68, s31, 31
	s_ashr_i32 s69, s30, 31
	v_mov_b32_e32 v161, v155
	v_mov_b32_e32 v163, v155
	v_mov_b64_e32 v[164:165], 0x200
	v_mov_b64_e32 v[166:167], 0x1ff
	v_add_u32_e32 v189, s70, v187
	v_add_u32_e32 v190, s71, v187
	v_add_u32_e32 v191, 0, v1
	v_mbcnt_hi_u32_b32 v192, -1, v0
	s_mov_b32 s72, 0
	s_barrier
	s_branch .LBB0_789

.LBB0_873:
	s_lshl_b32 s6, s6, 5
	s_and_b32 s12, s6, 0x60
	s_mov_b64 s[6:7], 0x80
	s_add_i32 m0, s19, 0x18000
	v_lshl_add_u64 v[6:7], v[6:7], 0, s[6:7]
	s_lshl_b32 s9, s8, 13
	s_lshl_b32 s13, s12, 7
	global_load_lds_dwordx4 v[6:7], off
	v_lshl_add_u64 v[4:5], v[4:5], 0, s[6:7]
	s_add_i32 m0, s19, 0x1a000
	s_add_i32 s51, s19, 0x8000
	s_add_i32 s64, s19, 0xa000
	global_load_lds_dwordx4 v[4:5], off
	v_lshl_add_u64 v[0:1], v[0:1], 0, s[6:7]
	s_mov_b32 m0, s51
	s_add_u32 s10, s24, 0x40080
	global_load_lds_dwordx4 v[0:1], off
	v_lshl_add_u64 v[0:1], v[2:3], 0, s[6:7]
	s_mov_b32 m0, s64
	s_addc_u32 s11, s25, 0
	global_load_lds_dwordx4 v[0:1], off
	s_add_i32 m0, s19, 0x1c000
	v_lshl_add_u64 v[0:1], s[10:11], 0, v[132:133]
	global_load_lds_dwordx4 v[0:1], off
	v_lshl_add_u64 v[0:1], s[10:11], 0, v[128:129]
	s_add_i32 m0, s19, 0x1e000
	v_bfe_u32 v2, v196, 4, 2
	global_load_lds_dwordx4 v[0:1], off
	v_and_b32_e32 v1, 15, v196
	v_lshlrev_b32_e32 v0, 4, v2
	v_lshlrev_b32_e32 v3, 2, v196
	v_lshl_or_b32 v149, s8, 6, v1
	v_lshl_or_b32 v1, v1, 6, v0
	v_and_b32_e32 v3, 32, v3
	s_sext_i32_i16 s69, s0
	v_bitop3_b32 v4, v1, s9, v3 bitop3:0xde
	v_lshlrev_b32_e32 v1, 6, v196
	s_movk_i32 s0, 0x3c0
	v_and_or_b32 v1, v1, s0, v0
	v_bitop3_b32 v150, s13, v1, v3 bitop3:0xf6
	v_mov_b32_e32 v1, v133
	v_lshl_add_u64 v[136:137], s[34:35], 0, v[0:1]
	v_lshlrev_b32_e32 v0, 8, v196
	v_and_b32_e32 v0, 0x38000, v0
	v_lshlrev_b32_e32 v1, 11, v11
	v_or3_b32 v0, v9, v0, v1
	v_add_u32_e32 v138, v0, v10
	v_lshlrev_b32_e32 v0, 4, v8
	v_and_b32_e32 v0, 0x78000, v0
	s_waitcnt vmcnt(8)
	s_barrier
	s_waitcnt vmcnt(6)
	s_cmpk_lt_u32 s1, 0x100
	v_or3_b32 v0, v9, v0, v1
	s_cselect_b64 s[8:9], -1, 0
	v_add_u32_e32 v140, v0, v10
	s_add_i32 s66, 0, 0x10000
	s_add_i32 s67, 0, 0x14000
	v_mbcnt_lo_u32_b32 v0, -1, 0
	v_or_b32_e32 v151, 16, v149
	v_or_b32_e32 v152, 32, v149
	v_or_b32_e32 v153, 48, v149
	s_ashr_i32 s65, s31, 31
	v_lshl_or_b32 v154, v2, 3, s12
	v_mov_b32_e32 v139, v133
	v_mov_b32_e32 v141, v133
	v_mov_b64_e32 v[142:143], 0xb00
	v_mov_b64_e32 v[144:145], 0xaff
	v_add_u32_e32 v155, s66, v150
	v_add_u32_e32 v156, s67, v150
	v_add_u32_e32 v157, 0, v4
	v_mbcnt_hi_u32_b32 v158, -1, v0
	v_mov_b32_e32 v159, 0x358637bd
	s_movk_i32 s68, 0x1600
	s_barrier
	s_branch .LBB0_876

.LBB0_946:
	s_mov_b64 s[12:13], 0x80
	s_and_b32 s47, s1, 3
	s_add_i32 m0, s29, 0x18000
	v_lshl_add_u64 v[6:7], v[6:7], 0, s[12:13]
	s_lshl_b32 s1, s0, 13
	s_lshl_b32 s5, s47, 12
	global_load_lds_dwordx4 v[6:7], off
	v_lshl_add_u64 v[4:5], v[4:5], 0, s[12:13]
	s_add_i32 m0, s29, 0x1a000
	s_add_i32 s48, s29, 0x8000
	s_add_i32 s49, s29, 0xa000
	global_load_lds_dwordx4 v[4:5], off
	v_lshl_add_u64 v[0:1], v[0:1], 0, s[12:13]
	s_mov_b32 m0, s48
	s_add_u32 s2, s22, 0xb0080
	global_load_lds_dwordx4 v[0:1], off
	v_lshl_add_u64 v[0:1], v[2:3], 0, s[12:13]
	s_mov_b32 m0, s49
	s_addc_u32 s3, s23, 0
	global_load_lds_dwordx4 v[0:1], off
	s_add_i32 m0, s29, 0x1c000
	v_lshl_add_u64 v[0:1], s[2:3], 0, v[154:155]
	global_load_lds_dwordx4 v[0:1], off
	v_lshl_add_u64 v[0:1], s[2:3], 0, v[158:159]
	s_add_i32 m0, s29, 0x1e000
	v_lshlrev_b32_e32 v4, 2, v196
	global_load_lds_dwordx4 v[0:1], off
	v_bfe_u32 v0, v196, 4, 2
	v_and_b32_e32 v1, 15, v196
	v_lshlrev_b32_e32 v3, 4, v0
	s_waitcnt vmcnt(0)
	v_lshl_or_b32 v186, s0, 6, v1
	v_lshl_or_b32 v1, v1, 6, v3
	v_and_b32_e32 v4, 32, v4
	v_lshlrev_b32_e32 v5, 6, v196
	s_movk_i32 s0, 0x3c0
	v_lshlrev_b32_e32 v2, 3, v0
	v_bitop3_b32 v1, v1, s1, v4 bitop3:0xde
	v_and_or_b32 v3, v5, s0, v3
	v_cmp_eq_u32_e64 s[0:1], 0, v0
	v_add_u16_e32 v0, v8, v9
	s_waitcnt vmcnt(8)
	s_barrier
	s_waitcnt vmcnt(6)
	s_cmpk_lt_u32 s4, 0x100
	v_lshrrev_b16_e32 v0, 1, v0
	v_bitop3_b32 v187, s5, v3, v4 bitop3:0xf6
	s_cselect_b64 s[14:15], -1, 0
	v_add_lshl_u32 v160, v10, v0, 1
	v_add_lshl_u32 v162, v11, v0, 1
	s_add_i32 s64, 0, 0x10000
	s_add_i32 s65, 0, 0x14000
	v_mbcnt_lo_u32_b32 v0, -1, 0
	v_lshl_or_b32 v188, s47, 5, v2
	s_ashr_i32 s50, s31, 31
	s_ashr_i32 s51, s30, 31
	v_mov_b32_e32 v161, v155
	v_mov_b32_e32 v163, v155
	v_mov_b64_e32 v[164:165], 0x200
	v_mov_b64_e32 v[166:167], 0x1ff
	v_add_u32_e32 v189, s64, v187
	v_add_u32_e32 v190, s65, v187
	v_add_u32_e32 v191, 0, v1
	v_mbcnt_hi_u32_b32 v192, -1, v0
	s_mov_b32 s66, 0
	s_barrier
	s_branch .LBB0_949

.LBB0_1043:
	s_mov_b64 s[12:13], 0x80
	s_add_i32 m0, s70, 0x18000
	v_lshl_add_u64 v[6:7], v[6:7], 0, s[12:13]
	s_and_b32 s2, s0, 3
	s_lshl_b32 s75, s68, 6
	s_lshl_b32 s3, s68, 13
	global_load_lds_dwordx4 v[6:7], off
	v_lshl_add_u64 v[4:5], v[4:5], 0, s[12:13]
	s_add_i32 m0, s70, 0x1a000
	s_add_i32 s76, s70, 0x8000
	s_add_i32 s77, s70, 0xa000
	global_load_lds_dwordx4 v[4:5], off
	v_lshl_add_u64 v[0:1], v[0:1], 0, s[12:13]
	s_mov_b32 m0, s76
	s_add_u32 s0, s46, 0x40080
	global_load_lds_dwordx4 v[0:1], off
	v_lshl_add_u64 v[0:1], v[2:3], 0, s[12:13]
	s_mov_b32 m0, s77
	s_addc_u32 s1, s47, 0
	global_load_lds_dwordx4 v[0:1], off
	s_add_i32 m0, s70, 0x1c000
	v_lshl_add_u64 v[0:1], s[0:1], 0, v[162:163]
	global_load_lds_dwordx4 v[0:1], off
	v_lshl_add_u64 v[0:1], s[0:1], 0, v[166:167]
	s_add_i32 m0, s70, 0x1e000
	s_cmpk_lt_u32 s16, 0x100
	global_load_lds_dwordx4 v[0:1], off
	v_lshlrev_b32_e32 v1, 2, v218
	v_lshl_or_b32 v0, v218, 6, v168
	v_and_b32_e32 v1, 32, v1
	v_bitop3_b32 v0, v0, s3, v1 bitop3:0xde
	v_lshlrev_b32_e32 v1, 8, v196
	v_and_b32_e32 v1, 0x38000, v1
	v_lshlrev_b32_e32 v2, 11, v215
	s_cselect_b64 s[14:15], -1, 0
	s_bitcmp0_b32 s16, 6
	v_or3_b32 v1, v197, v1, v2
	s_cselect_b64 s[16:17], -1, 0
	s_ashr_i32 s78, s31, 31
	s_ashr_i32 s79, s30, 31
	s_waitcnt vmcnt(0)
	v_add_u32_e32 v174, v1, v214
	v_lshlrev_b32_e32 v1, 4, v216
	s_waitcnt vmcnt(8)
	s_barrier
	s_waitcnt vmcnt(6)
	s_cmp_lg_u64 s[6:7], 0
	v_and_b32_e32 v1, 0x78000, v1
	v_lshl_or_b32 v221, s2, 12, v219
	s_cselect_b64 s[18:19], -1, 0
	v_mov_b32_e32 v169, v171
	v_or3_b32 v1, v197, v1, v2
	s_add_i32 s82, 0, 0x10000
	s_add_i32 s83, 0, 0x14000
	v_add_u32_e32 v225, 0, v0
	v_mbcnt_lo_u32_b32 v0, -1, 0
	v_cmp_eq_u32_e64 s[0:1], 0, v218
	v_lshl_add_u64 v[172:173], s[34:35], 0, v[168:169]
	v_lshl_or_b32 v169, s2, 5, v217
	v_mov_b32_e32 v175, v171
	v_add_u32_e32 v176, v1, v214
	v_mov_b32_e32 v177, v171
	v_mov_b64_e32 v[178:179], 0x400
	v_mov_b64_e32 v[180:181], 0x3ff
	v_add_u32_e32 v222, s82, v221
	v_add_u32_e32 v223, s83, v221
	v_mbcnt_hi_u32_b32 v226, -1, v0
	v_mov_b32_e32 v227, 0x358637bd
	s_barrier
	s_branch .LBB0_1046

.LBB0_1351:
	s_lshl_b32 s4, s4, 5
	s_and_b32 s14, s4, 0x60
	s_mov_b64 s[4:5], 0x80
	s_add_i32 m0, s23, 0x18000
	v_lshl_add_u64 v[6:7], v[6:7], 0, s[4:5]
	s_lshl_b32 s11, s10, 13
	global_load_lds_dwordx4 v[6:7], off
	v_lshl_add_u64 v[4:5], v[4:5], 0, s[4:5]
	s_add_i32 m0, s23, 0x1a000
	s_add_i32 s65, s23, 0x8000
	s_add_i32 s66, s23, 0xa000
	global_load_lds_dwordx4 v[4:5], off
	v_lshl_add_u64 v[0:1], v[0:1], 0, s[4:5]
	s_mov_b32 m0, s65
	s_add_u32 s12, s26, 0x40080
	global_load_lds_dwordx4 v[0:1], off
	v_lshl_add_u64 v[0:1], v[2:3], 0, s[4:5]
	s_mov_b32 m0, s66
	s_addc_u32 s13, s27, 0
	global_load_lds_dwordx4 v[0:1], off
	s_add_i32 m0, s23, 0x1c000
	v_lshl_add_u64 v[0:1], s[12:13], 0, v[162:163]
	global_load_lds_dwordx4 v[0:1], off
	v_lshl_add_u64 v[0:1], s[12:13], 0, v[166:167]
	s_add_i32 m0, s23, 0x1e000
	v_lshlrev_b32_e32 v2, 11, v215
	global_load_lds_dwordx4 v[0:1], off
	v_lshlrev_b32_e32 v1, 2, v218
	v_lshl_or_b32 v0, v218, 6, v168
	v_and_b32_e32 v1, 32, v1
	v_bitop3_b32 v0, v0, s11, v1 bitop3:0xde
	v_lshlrev_b32_e32 v1, 8, v196
	v_and_b32_e32 v1, 0x38000, v1
	v_or3_b32 v1, v197, v1, v2
	v_add_u32_e32 v130, v1, v214
	v_lshlrev_b32_e32 v1, 4, v216
	s_waitcnt vmcnt(8)
	s_barrier
	s_waitcnt vmcnt(6)
	s_cmpk_lt_u32 s1, 0x100
	v_and_b32_e32 v1, 0x78000, v1
	v_lshl_or_b32 v141, s10, 6, v218
	v_lshl_or_b32 v142, s14, 7, v219
	s_cselect_b64 s[10:11], -1, 0
	v_mov_b32_e32 v169, v163
	v_or3_b32 v1, v197, v1, v2
	s_add_i32 s68, 0, 0x10000
	s_add_i32 s69, 0, 0x14000
	v_add_u32_e32 v149, 0, v0
	v_mbcnt_lo_u32_b32 v0, -1, 0
	s_sext_i32_i16 s71, s0
	v_or_b32_e32 v143, 16, v141
	v_or_b32_e32 v144, 32, v141
	v_or_b32_e32 v145, 48, v141
	s_ashr_i32 s67, s31, 31
	v_lshl_add_u64 v[128:129], s[34:35], 0, v[168:169]
	v_or_b32_e32 v146, s14, v217
	v_mov_b32_e32 v131, v163
	v_add_u32_e32 v132, v1, v214
	v_mov_b32_e32 v133, v163
	v_mov_b64_e32 v[134:135], 0xb00
	v_mov_b64_e32 v[136:137], 0xaff
	v_add_u32_e32 v147, s68, v142
	v_add_u32_e32 v148, s69, v142
	v_mbcnt_hi_u32_b32 v150, -1, v0
	v_mov_b32_e32 v151, 0x358637bd
	s_movk_i32 s70, 0x1600
	s_barrier
	s_branch .LBB0_1354

.LBB0_1424:
	s_mov_b64 s[14:15], 0x80
	s_and_b32 s49, s1, 3
	s_add_i32 m0, s45, 0x18000
	v_lshl_add_u64 v[6:7], v[6:7], 0, s[14:15]
	s_lshl_b32 s1, s0, 13
	s_lshl_b32 s5, s49, 12
	global_load_lds_dwordx4 v[6:7], off
	v_lshl_add_u64 v[4:5], v[4:5], 0, s[14:15]
	s_add_i32 m0, s45, 0x1a000
	s_add_i32 s50, s45, 0x8000
	s_add_i32 s51, s45, 0xa000
	global_load_lds_dwordx4 v[4:5], off
	v_lshl_add_u64 v[0:1], v[0:1], 0, s[14:15]
	s_mov_b32 m0, s50
	s_add_u32 s2, s24, 0xb0080
	global_load_lds_dwordx4 v[0:1], off
	v_lshl_add_u64 v[0:1], v[2:3], 0, s[14:15]
	s_mov_b32 m0, s51
	s_addc_u32 s3, s25, 0
	global_load_lds_dwordx4 v[0:1], off
	s_add_i32 m0, s45, 0x1c000
	v_lshl_add_u64 v[0:1], s[2:3], 0, v[154:155]
	global_load_lds_dwordx4 v[0:1], off
	v_lshl_add_u64 v[0:1], s[2:3], 0, v[158:159]
	s_add_i32 m0, s45, 0x1e000
	v_lshlrev_b32_e32 v4, 2, v196
	global_load_lds_dwordx4 v[0:1], off
	v_bfe_u32 v0, v196, 4, 2
	v_and_b32_e32 v1, 15, v196
	v_lshlrev_b32_e32 v3, 4, v0
	s_waitcnt vmcnt(0)
	v_lshl_or_b32 v186, s0, 6, v1
	v_lshl_or_b32 v1, v1, 6, v3
	v_and_b32_e32 v4, 32, v4
	v_lshlrev_b32_e32 v5, 6, v196
	s_movk_i32 s0, 0x3c0
	v_lshlrev_b32_e32 v2, 3, v0
	v_bitop3_b32 v1, v1, s1, v4 bitop3:0xde
	v_and_or_b32 v3, v5, s0, v3
	v_cmp_eq_u32_e64 s[0:1], 0, v0
	v_add_u16_e32 v0, v8, v9
	s_waitcnt vmcnt(8)
	s_barrier
	s_waitcnt vmcnt(6)
	s_cmpk_lt_u32 s4, 0x100
	v_lshrrev_b16_e32 v0, 1, v0
	v_bitop3_b32 v187, s5, v3, v4 bitop3:0xf6
	s_cselect_b64 s[16:17], -1, 0
	v_add_lshl_u32 v160, v10, v0, 1
	v_add_lshl_u32 v162, v11, v0, 1
	s_add_i32 s66, 0, 0x10000
	s_add_i32 s67, 0, 0x14000
	v_mbcnt_lo_u32_b32 v0, -1, 0
	v_lshl_or_b32 v188, s49, 5, v2
	s_ashr_i32 s64, s31, 31
	s_ashr_i32 s65, s30, 31
	v_mov_b32_e32 v161, v155
	v_mov_b32_e32 v163, v155
	v_mov_b64_e32 v[164:165], 0x200
	v_mov_b64_e32 v[166:167], 0x1ff
	v_add_u32_e32 v189, s66, v187
	v_add_u32_e32 v190, s67, v187
	v_add_u32_e32 v191, 0, v1
	v_mbcnt_hi_u32_b32 v192, -1, v0
	s_mov_b32 s68, 0
	s_barrier
	s_branch .LBB0_1427

.LBB0_1524:
	s_mov_b64 s[10:11], 0x80
	s_and_b32 s3, s0, 3
	s_add_i32 m0, s49, 0x18000
	v_lshl_add_u64 v[6:7], v[6:7], 0, s[10:11]
	s_lshl_b32 s66, s1, 6
	s_lshl_b32 s12, s1, 13
	s_lshl_b32 s13, s3, 12
	global_load_lds_dwordx4 v[6:7], off
	v_lshl_add_u64 v[4:5], v[4:5], 0, s[10:11]
	s_add_i32 m0, s49, 0x1a000
	s_add_i32 s67, s49, 0x8000
	s_add_i32 s68, s49, 0xa000
	global_load_lds_dwordx4 v[4:5], off
	v_lshl_add_u64 v[0:1], v[0:1], 0, s[10:11]
	s_mov_b32 m0, s67
	s_add_u32 s0, s28, 0x40080
	global_load_lds_dwordx4 v[0:1], off
	v_lshl_add_u64 v[0:1], v[2:3], 0, s[10:11]
	s_mov_b32 m0, s68
	s_addc_u32 s1, s29, 0
	global_load_lds_dwordx4 v[0:1], off
	s_add_i32 m0, s49, 0x1c000
	v_lshl_add_u64 v[0:1], s[0:1], 0, v[162:163]
	global_load_lds_dwordx4 v[0:1], off
	v_lshl_add_u64 v[0:1], s[0:1], 0, v[166:167]
	s_add_i32 m0, s49, 0x1e000
	v_bfe_u32 v193, v196, 4, 2
	global_load_lds_dwordx4 v[0:1], off
	v_and_b32_e32 v192, 15, v196
	v_lshlrev_b32_e32 v0, 3, v193
	v_lshlrev_b32_e32 v168, 4, v193
	v_lshlrev_b32_e32 v2, 2, v196
	v_lshlrev_b32_e32 v3, 6, v196
	s_movk_i32 s0, 0x3c0
	v_lshl_or_b32 v1, v192, 6, v168
	v_and_b32_e32 v2, 32, v2
	v_and_or_b32 v3, v3, s0, v168
	v_lshl_or_b32 v195, s3, 5, v0
	v_lshlrev_b32_e32 v0, 8, v196
	v_bitop3_b32 v1, v1, s12, v2 bitop3:0xde
	v_bitop3_b32 v194, s13, v3, v2 bitop3:0xf6
	v_and_b32_e32 v0, 0x38000, v0
	v_lshlrev_b32_e32 v2, 11, v10
	v_or3_b32 v0, v8, v0, v2
	v_add_u32_e32 v172, v0, v9
	v_lshlrev_b32_e32 v0, 4, v11
	s_cmpk_lt_u32 s14, 0x100
	v_and_b32_e32 v0, 0x78000, v0
	s_waitcnt vmcnt(8)
	s_barrier
	s_waitcnt vmcnt(6)
	s_cselect_b64 s[12:13], -1, 0
	s_bitcmp0_b32 s14, 6
	v_or3_b32 v0, v8, v0, v2
	s_cselect_b64 s[14:15], -1, 0
	v_add_u32_e32 v174, v0, v9
	s_add_i32 s71, 0, 0x10000
	s_add_i32 s72, 0, 0x14000
	v_mbcnt_lo_u32_b32 v0, -1, 0
	s_ashr_i32 s69, s31, 31
	s_ashr_i32 s70, s30, 31
	v_lshl_add_u64 v[170:171], s[34:35], 0, v[168:169]
	v_mov_b32_e32 v173, v169
	v_mov_b32_e32 v175, v169
	v_mov_b64_e32 v[176:177], 0x200
	v_mov_b64_e32 v[178:179], 0x1ff
	v_add_u32_e32 v197, s71, v194
	v_add_u32_e32 v198, s72, v194
	v_add_u32_e32 v199, 0, v1
	v_mbcnt_hi_u32_b32 v200, -1, v0
	v_mov_b32_e32 v201, 0x358637bd
	v_mov_b32_e32 v202, 0x3e38aa3b
	s_barrier
	s_branch .LBB0_1527

.LBB0_2030:
	s_mov_b64 s[10:11], 0x80
	s_and_b32 s47, s1, 3
	s_add_i32 m0, s43, 0x18000
	v_lshl_add_u64 v[6:7], v[6:7], 0, s[10:11]
	s_lshl_b32 s1, s0, 13
	s_lshl_b32 s13, s47, 12
	global_load_lds_dwordx4 v[6:7], off
	v_lshl_add_u64 v[4:5], v[4:5], 0, s[10:11]
	s_add_i32 m0, s43, 0x1a000
	s_add_i32 s48, s43, 0x8000
	s_add_i32 s49, s43, 0xa000
	global_load_lds_dwordx4 v[4:5], off
	v_lshl_add_u64 v[0:1], v[0:1], 0, s[10:11]
	s_mov_b32 m0, s48
	s_add_u32 s2, s26, 0x40080
	global_load_lds_dwordx4 v[0:1], off
	v_lshl_add_u64 v[0:1], v[2:3], 0, s[10:11]
	s_mov_b32 m0, s49
	s_addc_u32 s3, s27, 0
	global_load_lds_dwordx4 v[0:1], off
	s_add_i32 m0, s43, 0x1c000
	v_lshl_add_u64 v[0:1], s[2:3], 0, v[154:155]
	global_load_lds_dwordx4 v[0:1], off
	v_lshl_add_u64 v[0:1], s[2:3], 0, v[158:159]
	s_add_i32 m0, s43, 0x1e000
	v_lshlrev_b32_e32 v4, 2, v196
	global_load_lds_dwordx4 v[0:1], off
	v_bfe_u32 v0, v196, 4, 2
	v_and_b32_e32 v1, 15, v196
	v_lshlrev_b32_e32 v3, 4, v0
	s_waitcnt vmcnt(0)
	v_lshl_or_b32 v186, s0, 6, v1
	v_lshl_or_b32 v1, v1, 6, v3
	v_and_b32_e32 v4, 32, v4
	v_lshlrev_b32_e32 v5, 6, v196
	s_movk_i32 s0, 0x3c0
	v_lshlrev_b32_e32 v2, 3, v0
	v_bitop3_b32 v1, v1, s1, v4 bitop3:0xde
	v_and_or_b32 v3, v5, s0, v3
	v_cmp_eq_u32_e64 s[0:1], 0, v0
	v_lshlrev_b32_e32 v0, 8, v196
	v_lshl_or_b32 v188, s47, 5, v2
	v_and_b32_e32 v0, 0x38000, v0
	v_lshlrev_b32_e32 v2, 11, v10
	v_or3_b32 v0, v8, v0, v2
	v_add_u32_e32 v160, v0, v9
	v_lshlrev_b32_e32 v0, 4, v11
	v_and_b32_e32 v0, 0x78000, v0
	s_waitcnt vmcnt(8)
	s_barrier
	s_waitcnt vmcnt(6)
	s_cmpk_lt_u32 s12, 0x100
	v_or3_b32 v0, v8, v0, v2
	v_bitop3_b32 v187, s13, v3, v4 bitop3:0xf6
	s_cselect_b64 s[12:13], -1, 0
	v_add_u32_e32 v162, v0, v9
	s_add_i32 s64, 0, 0x10000
	s_add_i32 s65, 0, 0x14000
	v_mbcnt_lo_u32_b32 v0, -1, 0
	s_ashr_i32 s50, s31, 31
	s_ashr_i32 s51, s30, 31
	v_mov_b32_e32 v161, v155
	v_mov_b32_e32 v163, v155
	v_mov_b64_e32 v[164:165], 0x200
	v_mov_b64_e32 v[166:167], 0x1ff
	v_add_u32_e32 v189, s64, v187
	v_add_u32_e32 v190, s65, v187
	v_add_u32_e32 v191, 0, v1
	v_mbcnt_hi_u32_b32 v192, -1, v0
	s_mov_b32 s66, 0
	s_barrier
	s_branch .LBB0_2033

.LBB0_2117:
	s_lshl_b32 s6, s6, 5
	s_and_b32 s12, s6, 0x60
	s_mov_b64 s[6:7], 0x80
	s_add_i32 m0, s19, 0x18000
	v_lshl_add_u64 v[6:7], v[6:7], 0, s[6:7]
	s_lshl_b32 s9, s8, 13
	s_lshl_b32 s13, s12, 7
	global_load_lds_dwordx4 v[6:7], off
	v_lshl_add_u64 v[4:5], v[4:5], 0, s[6:7]
	s_add_i32 m0, s19, 0x1a000
	s_add_i32 s43, s19, 0x8000
	s_add_i32 s44, s19, 0xa000
	global_load_lds_dwordx4 v[4:5], off
	v_lshl_add_u64 v[0:1], v[0:1], 0, s[6:7]
	s_mov_b32 m0, s43
	s_add_u32 s10, s22, 0x40080
	global_load_lds_dwordx4 v[0:1], off
	v_lshl_add_u64 v[0:1], v[2:3], 0, s[6:7]
	s_mov_b32 m0, s44
	s_addc_u32 s11, s23, 0
	global_load_lds_dwordx4 v[0:1], off
	s_add_i32 m0, s19, 0x1c000
	v_lshl_add_u64 v[0:1], s[10:11], 0, v[132:133]
	global_load_lds_dwordx4 v[0:1], off
	v_lshl_add_u64 v[0:1], s[10:11], 0, v[128:129]
	s_add_i32 m0, s19, 0x1e000
	v_bfe_u32 v2, v196, 4, 2
	global_load_lds_dwordx4 v[0:1], off
	v_and_b32_e32 v1, 15, v196
	v_lshlrev_b32_e32 v0, 4, v2
	v_lshlrev_b32_e32 v3, 2, v196
	v_lshl_or_b32 v149, s8, 6, v1
	v_lshl_or_b32 v1, v1, 6, v0
	v_and_b32_e32 v3, 32, v3
	s_sext_i32_i16 s49, s0
	v_bitop3_b32 v4, v1, s9, v3 bitop3:0xde
	v_lshlrev_b32_e32 v1, 6, v196
	s_movk_i32 s0, 0x3c0
	v_and_or_b32 v1, v1, s0, v0
	v_bitop3_b32 v150, s13, v1, v3 bitop3:0xf6
	v_mov_b32_e32 v1, v133
	v_lshl_add_u64 v[136:137], s[34:35], 0, v[0:1]
	v_lshlrev_b32_e32 v0, 8, v196
	v_and_b32_e32 v0, 0x38000, v0
	v_lshlrev_b32_e32 v1, 11, v11
	v_or3_b32 v0, v9, v0, v1
	v_add_u32_e32 v138, v0, v10
	v_lshlrev_b32_e32 v0, 4, v8
	v_and_b32_e32 v0, 0x78000, v0
	s_waitcnt vmcnt(8)
	s_barrier
	s_waitcnt vmcnt(6)
	s_cmpk_lt_u32 s1, 0x100
	v_or3_b32 v0, v9, v0, v1
	s_cselect_b64 s[8:9], -1, 0
	v_add_u32_e32 v140, v0, v10
	s_add_i32 s46, 0, 0x10000
	s_add_i32 s47, 0, 0x14000
	v_mbcnt_lo_u32_b32 v0, -1, 0
	v_or_b32_e32 v151, 16, v149
	v_or_b32_e32 v152, 32, v149
	v_or_b32_e32 v153, 48, v149
	s_ashr_i32 s45, s31, 31
	v_lshl_or_b32 v154, v2, 3, s12
	v_mov_b32_e32 v139, v133
	v_mov_b32_e32 v141, v133
	v_mov_b64_e32 v[142:143], 0xb00
	v_mov_b64_e32 v[144:145], 0xaff
	v_add_u32_e32 v155, s46, v150
	v_add_u32_e32 v156, s47, v150
	v_add_u32_e32 v157, 0, v4
	v_mbcnt_hi_u32_b32 v158, -1, v0
	v_mov_b32_e32 v159, 0x358637bd
	s_movk_i32 s48, 0x1600
	s_barrier
	s_branch .LBB0_2120

.LBB0_2190:
	s_mov_b64 s[12:13], 0x80
	s_and_b32 s39, s1, 3
	s_add_i32 m0, s27, 0x18000
	v_lshl_add_u64 v[6:7], v[6:7], 0, s[12:13]
	s_lshl_b32 s1, s0, 13
	s_lshl_b32 s5, s39, 12
	global_load_lds_dwordx4 v[6:7], off
	v_lshl_add_u64 v[4:5], v[4:5], 0, s[12:13]
	s_add_i32 m0, s27, 0x1a000
	s_add_i32 s40, s27, 0x8000
	s_add_i32 s41, s27, 0xa000
	global_load_lds_dwordx4 v[4:5], off
	v_lshl_add_u64 v[0:1], v[0:1], 0, s[12:13]
	s_mov_b32 m0, s40
	s_add_u32 s2, s20, 0xb0080
	global_load_lds_dwordx4 v[0:1], off
	v_lshl_add_u64 v[0:1], v[2:3], 0, s[12:13]
	s_mov_b32 m0, s41
	s_addc_u32 s3, s21, 0
	global_load_lds_dwordx4 v[0:1], off
	s_add_i32 m0, s27, 0x1c000
	v_lshl_add_u64 v[0:1], s[2:3], 0, v[154:155]
	global_load_lds_dwordx4 v[0:1], off
	v_lshl_add_u64 v[0:1], s[2:3], 0, v[158:159]
	s_add_i32 m0, s27, 0x1e000
	v_lshlrev_b32_e32 v4, 2, v196
	global_load_lds_dwordx4 v[0:1], off
	v_bfe_u32 v0, v196, 4, 2
	v_and_b32_e32 v1, 15, v196
	v_lshlrev_b32_e32 v3, 4, v0
	s_waitcnt vmcnt(0)
	v_lshl_or_b32 v186, s0, 6, v1
	v_lshl_or_b32 v1, v1, 6, v3
	v_and_b32_e32 v4, 32, v4
	v_lshlrev_b32_e32 v5, 6, v196
	s_movk_i32 s0, 0x3c0
	v_lshlrev_b32_e32 v2, 3, v0
	v_bitop3_b32 v1, v1, s1, v4 bitop3:0xde
	v_and_or_b32 v3, v5, s0, v3
	v_cmp_eq_u32_e64 s[0:1], 0, v0
	v_add_u16_e32 v0, v8, v9
	s_waitcnt vmcnt(8)
	s_barrier
	s_waitcnt vmcnt(6)
	s_cmpk_lt_u32 s4, 0x100
	v_lshrrev_b16_e32 v0, 1, v0
	v_bitop3_b32 v187, s5, v3, v4 bitop3:0xf6
	s_cselect_b64 s[14:15], -1, 0
	v_add_lshl_u32 v160, v10, v0, 1
	v_add_lshl_u32 v162, v11, v0, 1
	s_add_i32 s44, 0, 0x10000
	s_add_i32 s45, 0, 0x14000
	v_mbcnt_lo_u32_b32 v0, -1, 0
	v_lshl_or_b32 v188, s39, 5, v2
	s_ashr_i32 s42, s31, 31
	s_ashr_i32 s43, s30, 31
	v_mov_b32_e32 v161, v155
	v_mov_b32_e32 v163, v155
	v_mov_b64_e32 v[164:165], 0x200
	v_mov_b64_e32 v[166:167], 0x1ff
	v_add_u32_e32 v189, s44, v187
	v_add_u32_e32 v190, s45, v187
	v_add_u32_e32 v191, 0, v1
	v_mbcnt_hi_u32_b32 v192, -1, v0
	s_mov_b32 s46, 0
	s_barrier
	s_branch .LBB0_2193
